# idx mask write-out: four per-query dword stores merged into one dwordx4 store per lane (store widening)
# speedup vs baseline: 1.0022x; 1.0010x over previous
; __device__ __forceinline__ void run(Frame& F, int qword) {
;     ...
;             if (lane <= ktmax) mrow[lane * 32 + 4 * wid + j] = wv;
.LBB0_1200:
	v_lshl_add_u32 v98, v136, 5, s51
	v_cmp_ge_i32_e64 s[4:5], s63, v136
	v_ashrrev_i32_e32 v99, 31, v98
	s_and_saveexec_b64 s[0:1], s[4:5]
	s_cbranch_execz .LBB0_1202
	v_lshl_add_u64 v[100:101], v[98:99], 2, s[38:39]
	v_mov_b32_e32 v248, v80

; __device__ __forceinline__ void run(Frame& F, int qword) {
;     ...
;             if (lane <= ktmax) mrow[lane * 32 + 4 * wid + j] = wv;
.LBB0_1229:
	s_and_saveexec_b64 s[0:1], s[4:5]
	s_cbranch_execz .LBB0_1231
	v_lshl_add_u64 v[64:65], v[98:99], 2, s[38:39]
	v_mov_b32_e32 v249, v80

; __device__ __forceinline__ void run(Frame& F, int qword) {
;     ...
;             if (lane <= ktmax) mrow[lane * 32 + 4 * wid + j] = wv;
.LBB0_1258:
	s_and_saveexec_b64 s[0:1], s[4:5]
	s_cbranch_execz .LBB0_1260
	v_lshl_add_u64 v[32:33], v[98:99], 2, s[38:39]
	v_mov_b32_e32 v250, v54

; __device__ __forceinline__ void run(Frame& F, int qword) {
;     ...
;             if (lane <= ktmax) mrow[lane * 32 + 4 * wid + j] = wv;
.LBB0_1287:
	s_and_saveexec_b64 s[0:1], s[4:5]
	s_xor_b64 s[0:1], exec, s[0:1]
	s_cbranch_execz .LBB0_1289
	v_lshl_add_u64 v[0:1], v[98:99], 2, s[38:39]
	v_mov_b32_e32 v251, v24
	global_store_dwordx4 v[0:1], v[248:251], off
